# k16 + gates computed row-block-locally as a pre-pass of the IN-GEMM phase, so DeltaNet prep no longer depends on the attention phase: grid barrier between attention and dnprep removed
# speedup vs baseline: 1.0108x; 1.0108x over previous
; __global__ void __launch_bounds__(512, 2) mk_fwd(Args a) {
;     ...
;     for (int ph = a.ph_lo; ph < a.ph_hi; ++ph) {
;         if (ph == PH_PER_LAYER || ph == 2 * PH_PER_LAYER - 1) continue;
;         run_phase(ph, lds);
;         if (ph + 1 < a.ph_hi) xcd_barrier(xb);
.LBB0_29:
	s_cmp_eq_u32 s100, 5
	s_cbranch_scc0 .Lnot5
	s_mov_b32 s100, 4
	s_branch .LBB0_22

; __global__ void __launch_bounds__(512, 2) mk_fwd(Args a) {
;     ...
;     for (int ph = a.ph_lo; ph < a.ph_hi; ++ph) {
;         if (ph == PH_PER_LAYER || ph == 2 * PH_PER_LAYER - 1) continue;
;         run_phase(ph, lds);
;         if (ph + 1 < a.ph_hi) xcd_barrier(xb);
;     }
.Lnorm29:
	s_add_i32 s2, s22, 1
	s_cmp_ge_i32 s2, s23
	s_cbranch_scc1 .LBB0_21
	v_readlane_b32 s3, v253, 0
	s_cmpk_lg_u32 s3, 0x100
	s_cbranch_scc1 .Lnoskip
	s_cmp_eq_u32 s22, 5
	s_cbranch_scc1 .Lskipbar
	s_cmp_eq_u32 s22, 19
	s_cbranch_scc0 .Lnoskip
.Lskipbar:
	s_waitcnt vmcnt(0) lgkmcnt(0)
	s_branch .LBB0_21

; __device__ __forceinline__ void run_phase(int ph, LAS unsigned char* lds) {
;     ...
;     const int l = ph / PH_PER_LAYER, p = ph % PH_PER_LAYER;
;     float* stats = (float*)(ws + OFF_STATS);
;     const float* mur = (const float*)(ws + OFF_MUR);
;     const float* mu_in = l > 0 ? mur + (size_t)((l - 1) * 3 + 2) * T_ * 2 : nullptr;
;     const float* mu0 = mur + (size_t)(l * 3 + 0) * T_ * 2; const float* mu1 = mur + (size_t)(l * 3 + 1) * T_ * 2;
;     float* st0 = stats + (size_t)(l * 3 + 0) * T_ * 32; float* st1 = stats + (size_t)(l * 3 + 1) * T_ * 32; float* st2 = stats + (size_t)(l * 3 + 2) * T_ * 32;
;     const float* ln_g = a.in[5]; const float* ln_b = a.in[6];
;     pg8::StaticOrder S;
;     switch (p) {
;     case 0: if (PH_ENABLED(0)) { if (l == 0) pro_part(a, tb, 0, 0, tb.bid, tb.G, lds); } break;
;     case 1: if (PH_ENABLED(1)) { pg8::Gemm g{(const bf16_t*)(ws + OFF_YB), (const bf16_t*)(ws + OFF_WGU0), T_, 2 * FF_, D_}; S.init(g.M, g.N, tb.G, tb.bid);
;         EpiGU E{(bf16_t*)(ws + OFF_H), mu_in, (const float*)(ws + OFF_C12GU0), (const float*)(ws + OFF_C12GU0) + 5632}; pg8::gemm_phase(tb, lds, g, S, E); } break;
;     case 2: if (PH_ENABLED(2)) { pg8::Gemm g{(const bf16_t*)(ws + OFF_H), (const bf16_t*)(ws + OFF_WDN0), T_, D_, FF_}; S.init(g.M, g.N, tb.G, tb.bid);
;         EpiRes E{nullptr, (bf16_t*)(ws + OFF_YB), mu_in, l > 0 ? ln_g + ((l - 1) * 3 + 2) * D_ : nullptr, l > 0 ? ln_b + ((l - 1) * 3 + 2) * D_ : nullptr, st0, 0.5f}; pg8::gemm_phase(tb, lds, g, S, E); } break;
;     case 3: if (PH_ENABLED(3)) phase_statsfin(a, tb, l * 3 + 0); break;
;     case 4: if (PH_ENABLED(4)) { pg8::Gemm g{(const bf16_t*)(ws + OFF_YB), (const bf16_t*)(ws + OFF_WIN), T_, NING_, D_}; S.init(g.M, g.N, tb.G, tb.bid);
;         EpiIn E{mu0, (const float*)(ws + OFF_C12IN), (const float*)(ws + OFF_C12IN) + 3584, (bf16_t*)(ws + OFF_QK), (bf16_t*)(ws + OFF_VT), (bf16_t*)(ws + OFF_PC), (bf16_t*)(ws + OFF_Z)}; pg8::gemm_phase(tb, lds, g, S, E);
;         } break;
;     case 5: if (PH_ENABLED(5)) { phase_gates(a, tb, l); phase_attn(a, tb, l, lds); } break;
;     case 6: if (PH_ENABLED(6)) phase_dnprep(a, tb, l, lds); break;
;     case 7: if (PH_ENABLED(7)) { phase_dnscan(a, tb, lds);
;         if (tb.bid >= 128) { pro_part(a, tb, l, 1, tb.bid - 128, tb.G - 128, lds); if (l == 0) pro_part(a, tb, 1, 0, tb.bid - 128, tb.G - 128, lds); } } break;
.LBB0_30:
	s_mul_hi_i32 s2, s22, 0x92492493
	s_add_i32 s2, s2, s22
	s_lshr_b32 s3, s2, 31
	s_ashr_i32 s2, s2, 3
	s_add_i32 s50, s2, s3
	s_mul_i32 s2, s50, 14
	s_mov_b64 s[6:7], s[22:23]
	s_sub_i32 s8, s22, s2
	s_movk_i32 s101, 0x37f
	s_cmpk_lg_u32 s56, 0x100
	s_cbranch_scc1 .Lsf_nohook
	s_cmp_eq_u32 s8, 3
	s_cbranch_scc1 .Lsf_hook
	s_cmp_eq_u32 s8, 10
	s_cbranch_scc1 .Lsf_hook
	s_cmp_eq_u32 s8, 13
	s_cbranch_scc1 .Lsf_hook
	s_cmp_eq_u32 s8, 4
	s_cbranch_scc0 .Lgp_no
	s_cmp_eq_u32 s100, 0
	s_cbranch_scc0 .Lgp_second
	s_mov_b32 s100, 3
	s_mov_b32 s8, 5
	s_branch .Lsf_nohook
.Lgp_second:
	s_cmp_lg_u32 s50, 1
	s_cbranch_scc1 .Lsf_nohook
	s_movk_i32 s101, 0x2ff
	s_branch .Lsf_nohook
.Lgp_no:
	s_cmp_lg_u32 s50, 1
	s_cbranch_scc1 .Lsf_nohook
	s_cmp_lg_u32 s100, 0
	s_cbranch_scc1 .Lsf_nohook
	s_cmp_eq_u32 s8, 4
	s_cbranch_scc0 .Lin_chk7
	s_movk_i32 s101, 0x2ff
	s_branch .Lsf_nohook

; __device__ __forceinline__ void phase_gates(ArgsRef a, const Tb tb, int l) {
;     ...
;     const int wv = tb.tid >> 6, lane = tb.tid & 63;
;     const int gw = tb.bid * 8 + wv, GW = tb.G * 8;
;     for (int t = gw; t < T_; t += GW) {
.LBB0_1185:
	s_and_b64 vcc, exec, s[2:3]
	s_mov_b32 s73, s65
	s_cbranch_vccz .LBB0_1255
	v_readlane_b32 s38, v254, 42
	v_ashrrev_i32_e32 v198, 6, v196
	s_lshl_b32 s16, s38, 3
	v_readlane_b32 s14, v254, 36
	s_movk_i32 s36, 0x3fff
	s_cmpk_lg_u32 s14, 0x100
	s_cbranch_scc1 .Lgt_std
	s_and_b32 s16, s38, 7
	s_lshl_b32 s16, s16, 3
	s_bfe_u32 s14, s38, 0x30003
	s_add_i32 s16, s16, s14
	s_lshl_b32 s16, s16, 8
	s_lshr_b32 s14, s38, 6
	s_lshl_b32 s14, s14, 6
	s_add_i32 s16, s16, s14
	s_add_i32 s36, s16, 63
.Lgt_std:
	s_waitcnt vmcnt(0)
	v_add_u32_e32 v77, s16, v198
	s_movk_i32 s2, 0x4000
	v_cmp_gt_i32_e32 vcc, s2, v77
	v_and_b32_e32 v76, 63, v196
	v_readlane_b32 s39, v254, 43
	s_and_saveexec_b64 s[12:13], vcc
	s_mov_b32 s30, 0x3fb8aa3b
	s_mov_b32 s31, 0x42ce8ed0
	s_mov_b32 s33, 0xc2b17218
	s_mov_b32 s34, 0xc2ce8ed0
	s_mov_b32 s35, 0x42b17218
	s_mov_b64 s[24:25], 0x3000
	s_mov_b64 s[26:27], 0x2000
	v_readlane_b32 s4, v254, 36
	v_readlane_b32 s40, v254, 40
	v_readlane_b32 s5, v254, 37
	v_readlane_b32 s41, v254, 41
	s_cmpk_lg_u32 s4, 0x100
	s_cbranch_scc1 .Lgp_dogates
	s_cmp_eq_u32 s100, 3
	s_cbranch_scc0 .LBB0_1195
; __device__ __forceinline__ float bflo(unsigned w) { return __uint_as_float(w << 16); }
; __device__ __forceinline__ float bfhi(unsigned w) { return __uint_as_float(w & 0xffff0000u); }
; __device__ __forceinline__ void phase_gates(ArgsRef a, const Tb tb, int l) {
;     ...
;     const int wv = tb.tid >> 6, lane = tb.tid & 63;
;     const int gw = tb.bid * 8 + wv, GW = tb.G * 8;
;     for (int t = gw; t < T_; t += GW) {
;         f32x4 y[4];
; #pragma unroll
;         for (int i = 0; i < 4; ++i) { const u32x2 rb = *(const u32x2*)(YBp + (size_t)t * D_ + i * 256 + lane * 4); y[i] = (f32x4){bflo(rb.x), bfhi(rb.x), bflo(rb.y), bfhi(rb.y)}; }
;         float mu, rstd; row_stats(stats, t, mu, rstd);
;         float s8[8];
; #pragma unroll
;         for (int j = 0; j < 8; ++j) { float s = 0.f;
; #pragma unroll
;             for (int i = 0; i < 4; ++i) { const f32x4 w = *(const f32x4*)(wg8 + j * 1024 + i * 256 + lane * 4); s += (y[i][0] * w[0] + y[i][1] * w[1]) + (y[i][2] * w[2] + y[i][3] * w[3]); }
.Lgp_dogates:
	s_cbranch_execz .LBB0_1195
	s_lshl_b32 s14, s4, 3
	s_cmpk_eq_u32 s4, 0x100
	s_cselect_b32 s14, 8, s14
	v_and_b32_e32 v0, 32, v196
	s_waitcnt lgkmcnt(0)
	s_add_u32 s10, s48, 0x2a1d000
	v_cmp_eq_u32_e64 s[2:3], 0, v0
	v_and_b32_e32 v0, 16, v196
	s_addc_u32 s11, s49, 0
	v_lshlrev_b32_e32 v180, 4, v76
	v_cmp_eq_u32_e64 s[4:5], 0, v0
	v_and_b32_e32 v0, 8, v196
	v_lshl_add_u64 v[4:5], s[10:11], 0, v[180:181]
	v_cmp_eq_u32_e64 s[6:7], 0, v0
	v_xor_b32_e32 v0, 32, v236
	s_mov_b64 s[18:19], 0x1000
	v_cmp_lt_i32_e32 vcc, v0, v239
	v_lshl_add_u64 v[14:15], v[4:5], 0, s[18:19]
	s_mov_b64 s[18:19], 0x1400
	v_cndmask_b32_e32 v0, v236, v0, vcc
	v_lshl_add_u64 v[16:17], v[4:5], 0, s[18:19]
	s_mov_b64 s[18:19], 0x1800
	v_lshlrev_b32_e32 v78, 2, v0
	v_xor_b32_e32 v0, 16, v236
	v_lshl_add_u64 v[18:19], v[4:5], 0, s[18:19]
	s_mov_b64 s[18:19], 0x1c00
	v_cmp_lt_i32_e32 vcc, v0, v239
	v_lshl_add_u64 v[20:21], v[4:5], 0, s[18:19]
	s_mov_b64 s[18:19], 0x2400
	v_cndmask_b32_e32 v0, v236, v0, vcc
	v_lshl_add_u64 v[24:25], v[4:5], 0, s[18:19]
	s_mov_b64 s[18:19], 0x2800
	v_lshlrev_b32_e32 v79, 2, v0
	v_xor_b32_e32 v0, 8, v236
	v_lshl_add_u64 v[26:27], v[4:5], 0, s[18:19]
	s_mov_b64 s[18:19], 0x2c00
	v_cmp_lt_i32_e32 vcc, v0, v239
	v_lshl_add_u64 v[28:29], v[4:5], 0, s[18:19]
	s_mov_b64 s[18:19], 0x3400
	v_cndmask_b32_e32 v0, v236, v0, vcc
	v_cmp_lt_i32_e32 vcc, v241, v239
	v_lshl_add_u64 v[32:33], v[4:5], 0, s[18:19]
	s_mov_b64 s[18:19], 0x3800
	v_lshlrev_b32_e32 v80, 2, v0
	v_cndmask_b32_e32 v0, v236, v241, vcc
	v_cmp_lt_i32_e32 vcc, v240, v239
	v_lshl_add_u64 v[34:35], v[4:5], 0, s[18:19]
	s_mov_b64 s[18:19], 0x3c00
	v_lshlrev_b32_e32 v81, 2, v0
	v_cndmask_b32_e32 v0, v236, v240, vcc
	v_cmp_lt_i32_e32 vcc, v237, v239
	v_lshl_add_u64 v[36:37], v[4:5], 0, s[18:19]
	s_mov_b64 s[18:19], 0x4000
	v_lshlrev_b32_e32 v82, 2, v0
	v_cndmask_b32_e32 v0, v236, v237, vcc
	v_lshl_add_u64 v[38:39], v[4:5], 0, s[18:19]
	s_mov_b64 s[18:19], 0x4400
	v_lshlrev_b32_e32 v83, 2, v0
	v_and_b32_e32 v0, 7, v196
	v_lshl_add_u64 v[40:41], v[4:5], 0, s[18:19]
	s_mov_b64 s[18:19], 0x4800
	v_cmp_eq_u32_e64 s[8:9], 0, v0
	v_lshrrev_b32_e32 v0, 1, v76
	v_mov_b32_e32 v1, v181
	v_lshl_add_u64 v[42:43], v[4:5], 0, s[18:19]
	s_mov_b64 s[18:19], 0x4c00
	v_lshl_add_u64 v[0:1], s[10:11], 0, v[0:1]
	s_mov_b64 s[10:11], 0x8000
	v_lshl_add_u64 v[44:45], v[4:5], 0, s[18:19]
	s_mov_b64 s[18:19], 0x5000
	v_lshl_add_u64 v[6:7], v[0:1], 0, s[10:11]
	s_mov_b64 s[10:11], 0x8020
	v_lshl_add_u64 v[46:47], v[4:5], 0, s[18:19]
	s_mov_b64 s[18:19], 0x5400
	v_lshl_add_u64 v[8:9], v[0:1], 0, s[10:11]
	v_readlane_b32 s10, v254, 19
	v_lshl_add_u64 v[48:49], v[4:5], 0, s[18:19]
	s_mov_b64 s[18:19], 0x5800
	v_readlane_b32 s11, v254, 20
	v_lshl_add_u64 v[50:51], v[4:5], 0, s[18:19]
	s_mov_b64 s[18:19], 0x5c00
	s_load_dwordx4 s[20:23], s[10:11], 0x48
	v_lshl_add_u64 v[52:53], v[4:5], 0, s[18:19]
	s_mov_b64 s[18:19], 0x6000
	s_lshl_b32 s10, s40, 2
	v_lshl_add_u64 v[54:55], v[4:5], 0, s[18:19]
	s_mov_b64 s[18:19], 0x6400
	v_lshrrev_b32_e32 v180, 3, v76
	s_ashr_i32 s11, s10, 31
	v_lshl_add_u64 v[56:57], v[4:5], 0, s[18:19]
	s_mov_b64 s[18:19], 0x6800
	v_lshl_add_u64 v[0:1], s[10:11], 0, v[180:181]
	v_lshl_add_u64 v[58:59], v[4:5], 0, s[18:19]
	s_mov_b64 s[18:19], 0x6c00
	v_lshlrev_b64 v[0:1], 2, v[0:1]
	v_lshl_add_u64 v[60:61], v[4:5], 0, s[18:19]
	s_mov_b64 s[18:19], 0x7000
	v_ashrrev_i32_e32 v199, 31, v198
	s_ashr_i32 s17, s16, 31
	s_waitcnt lgkmcnt(0)
	v_lshl_add_u64 v[10:11], s[22:23], 0, v[0:1]
	v_lshl_add_u64 v[12:13], s[20:21], 0, v[0:1]
	v_lshl_add_u64 v[62:63], v[4:5], 0, s[18:19]
	s_mov_b64 s[18:19], 0x7400
	v_lshl_add_u64 v[0:1], v[198:199], 0, s[16:17]
	v_lshl_add_u64 v[64:65], v[4:5], 0, s[18:19]
	s_mov_b64 s[18:19], 0x7800
	v_lshlrev_b64 v[2:3], 5, v[0:1]
	v_lshl_add_u64 v[66:67], v[4:5], 0, s[18:19]
	s_mov_b64 s[18:19], 0x7c00
	v_lshl_add_u64 v[2:3], s[48:49], 0, v[2:3]
	s_mov_b64 s[16:17], 0x36e5040
	s_ashr_i32 s15, s14, 31
	v_lshl_add_u64 v[68:69], v[4:5], 0, s[18:19]
	v_lshl_add_u64 v[70:71], v[2:3], 0, s[16:17]
	s_lshl_b64 s[16:17], s[14:15], 5
	v_readlane_b32 s18, v254, 31
	s_add_u32 s18, s18, s88
	v_readlane_b32 s19, v254, 32
	s_addc_u32 s19, s19, s89
	s_mov_b64 s[20:21], 0x376a500
	v_lshl_add_u64 v[72:73], v[0:1], 3, s[18:19]
	v_lshlrev_b64 v[0:1], 11, v[0:1]
	v_lshl_or_b32 v0, v76, 3, v0
	v_lshl_add_u64 v[0:1], s[48:49], 0, v[0:1]
	v_cmp_lt_u32_e64 s[10:11], 31, v76
	v_lshl_add_u64 v[22:23], v[4:5], 0, s[26:27]
	v_lshl_add_u64 v[30:31], v[4:5], 0, s[24:25]
	s_lshl_b64 s[18:19], s[14:15], 3
	v_lshl_add_u64 v[74:75], v[0:1], 0, s[20:21]
	s_lshl_b64 s[20:21], s[14:15], 11
	s_mov_b64 s[22:23], 0
	global_load_dwordx4 v[108:111], v[4:5], off
	global_load_dwordx4 v[112:115], v[4:5], off offset:1024
	global_load_dwordx4 v[116:119], v[4:5], off offset:2048
	global_load_dwordx4 v[120:123], v[4:5], off offset:3072
	global_load_dwordx4 v[124:127], v[14:15], off
	global_load_dwordx4 v[128:131], v[14:15], off offset:1024
	global_load_dwordx4 v[132:135], v[14:15], off offset:2048
	global_load_dwordx4 v[136:139], v[14:15], off offset:3072
	global_load_dwordx4 v[140:143], v[22:23], off
	global_load_dwordx4 v[144:147], v[22:23], off offset:1024
	global_load_dwordx4 v[148:151], v[22:23], off offset:2048
	global_load_dwordx4 v[152:155], v[22:23], off offset:3072
	global_load_dwordx4 v[156:159], v[30:31], off
	global_load_dwordx4 v[160:163], v[30:31], off offset:1024
	global_load_dwordx4 v[164:167], v[30:31], off offset:2048
	global_load_dwordx4 v[168:171], v[30:31], off offset:3072
	global_load_dwordx4 v[172:175], v[38:39], off
	global_load_dwordx4 v[176:179], v[38:39], off offset:1024
	global_load_dwordx4 v[204:207], v[38:39], off offset:2048
	global_load_dwordx4 v[208:211], v[38:39], off offset:3072
	global_load_dwordx4 v[212:215], v[46:47], off
	global_load_dwordx4 v[216:219], v[46:47], off offset:1024
	global_load_dwordx4 v[220:223], v[46:47], off offset:2048
	global_load_dwordx4 v[224:227], v[46:47], off offset:3072
	global_load_dwordx4 v[228:231], v[54:55], off
	global_load_dwordx4 v[232:235], v[54:55], off offset:1024
	global_load_dwordx4 v[16:19], v[54:55], off offset:2048
	global_load_dwordx4 v[24:27], v[54:55], off offset:3072
	global_load_dwordx4 v[32:35], v[62:63], off
	global_load_dwordx4 v[40:43], v[62:63], off offset:1024
	global_load_dwordx4 v[48:51], v[62:63], off offset:2048
	global_load_dwordx4 v[56:59], v[62:63], off offset:3072
	s_and_saveexec_b64 s[24:25], s[8:9]
	global_load_dword v60, v[6:7], off
	global_load_dword v61, v[8:9], off
	s_and_b64 exec, exec, s[10:11]
	global_load_dword v68, v[10:11], off offset:-16
	global_load_dword v69, v[12:13], off offset:-16
	s_mov_b64 exec, s[24:25]
	s_branch .LBB0_1190

; #define LAS __attribute__((address_space(3)))
; __device__ __forceinline__ void phase_attn(ArgsRef a, const Tb tb, int l, LAS unsigned char* lds) {
;     unsigned char* ws = a.ws;
;     const bf16_t* QK = (const bf16_t*)(ws + OFF_QK); const bf16_t* VT = (const bf16_t*)(ws + OFF_VT); bf16_t* O = (bf16_t*)(ws + OFF_O);
;     const int lane = tb.tid & 63;
;     const float lambda_init = 0.8f - 0.6f * expf(-0.3f * (float)l);
;     const float* dl = a.in[12] + l * 128;
;     float p01 = 0.f, p23 = 0.f;
;     if (lane < 32) { p01 = dl[lane] * dl[32 + lane]; p23 = dl[64 + lane] * dl[96 + lane]; }
;     p01 = wave_sum(p01); p23 = wave_sum(p23);
;     const float lam = expf(p01) - expf(p23) + lambda_init;
.LBB0_1195:
	s_or_b64 exec, exec, s[12:13]
	s_cmp_eq_u32 s100, 3
	s_cbranch_scc0 .Lgp_cont
	s_mov_b32 s100, 5
	s_branch .LBB0_1647
.Lgp_cont:
	v_cmp_gt_u32_e32 vcc, 32, v76
	v_mov_b32_e32 v0, 0
	s_waitcnt lgkmcnt(0)
	v_mov_b32_e32 v1, 0
	s_and_saveexec_b64 s[2:3], vcc
	s_cbranch_execz .LBB0_1197
	v_readlane_b32 s4, v254, 19
	v_readlane_b32 s5, v254, 20
	s_load_dwordx2 s[4:5], s[4:5], 0x60
	s_lshl_b32 s6, s40, 7
	s_ashr_i32 s7, s6, 31
	s_lshl_b64 s[6:7], s[6:7], 2
	v_lshlrev_b32_e32 v2, 2, v76
	s_waitcnt lgkmcnt(0)
	s_add_u32 s4, s4, s6
	s_addc_u32 s5, s5, s7
	global_load_dword v1, v2, s[4:5]
	global_load_dword v3, v2, s[4:5] offset:128
	global_load_dword v0, v2, s[4:5] offset:256
	s_nop 0
	global_load_dword v2, v2, s[4:5] offset:384
	s_waitcnt vmcnt(0)
	v_pk_mul_f32 v[0:1], v[0:1], v[2:3]
